# attention tile loop edge: next-tile scalar bookkeeping, DMA bases and exit/wait-variant tests moved into the last PV MFMA shadow before the barrier; diamond flag branches collapsed
# baseline (speedup 1.0000x reference)
; template <bool FIXED> __device__ __forceinline__ void attn_unit(int b, int h, int qb, const bf16* __restrict__ P, bf16* __restrict__ MIX, const float* __restrict__ BT, const float* __restrict__ subg, ...
;     ...
;   float* ws = (float*)(lds + LDS_WS) + wid * 64; float* li_l = ws; float* al_l = ws + 32;
;   float* btl = (float*)(lds + LDS_BT);
;   for (int i = tid; i < 768; i += 512) btl[i] = BT[(size_t)h * 768 + i] - (FIXED ? sref : 0.f);
;   const float* bt = btl + m * 384 + 128;
;   const float c31 = BT[(size_t)h * 768 + m * 384 + 128 + 127] - (FIXED ? sref : 0.f);
;   f32x16 cfar, czero = f32x16{};
; #pragma unroll
;   for (int r = 0; r < 16; ++r) cfar[r] = FIXED ? c31 : 0.f;
;   float m_reg = -1e30f, l_reg = 0.f; f32x16 o[4] = {}; bf16x8 qr[4];
;   const bf16* Qw = P + (rowbase + qw0 + r32) * PW + h * 128 + m * 64 + hi * 8;
; #pragma unroll
;   for (int d0 = 0; d0 < 4; ++d0) qr[d0] = *reinterpret_cast<const bf16x8*>(Qw + d0 * 16);
;   const bf16* Kh = P + rowbase * PW + 1024 + h * 128; const bf16* Vh = P + rowbase * PW + 2048 + h * 128;
;   unsigned ksrc[2], vsrc[2];
; #pragma unroll
;   for (int i = 0; i < 2; ++i) { const int pk = wid * 2 + i;
;     { const int row = 4 * pk + (lane >> 4), cc = lane & 15; ksrc[i] = (unsigned)(row * PW + ((cc ^ (row & 7)) * 8)); }
;     { const int ob = pk * 1024 + lane * 16, sub = ob >> 9, kk = (sub >> 2) * 8 + ((ob & 511) >> 6), k = (kk & ~0xC) | ((kk & 4) << 1) | ((kk & 8) >> 1), c = (sub & 3) * 32 + ((ob & 63) >> 1);
;       vsrc[i] = (unsigned)(k * PW + c); } }
;   typedef __attribute__((address_space(3))) unsigned lds_u32;
;   typedef __attribute__((address_space(3))) unsigned char lds_u8;
;   lds_u8* const ring = (lds_u8*)lds + wid * 2048;
;     ...
;   const lds_cptr vp0 = (lds_cptr)lds + SHM_K + v_rd_base(lane);
;     ...
;   f32x16 p0, p1; float al, ca; bf16x8 pa0, pa1, pa2, pa3; const int NT = 2 * qb + 2;
;     ...
;   const int NTT = ATT_REP * NT;
;   DMA_TILE(0, 0); DMA_TILE(1, 1);
;   WAIT_BAR(4);
; __global__ void __launch_bounds__(NWAVES * 64, 2) hybrid_fwd(Args args) {
;     ...
;                     float bm = fmaxf(fmaxf(BT[hh * 768 + 128 + lane], BT[hh * 768 + 128 + 64 + lane]), fmaxf(BT[hh * 768 + 384 + 128 + lane], BT[hh * 768 + 384 + 128 + 64 + lane]));
; #pragma unroll
;                     for (int o = 1; o < 64; o <<= 1) bm = fmaxf(bm, __shfl_xor(bm, o));
;                     const float sref = 11.8f * gqk + bm + 0.25f;
.Lmy_t0_3:
	s_add_i32 m0, s99, 0
	v_lshl_add_u64 v[80:81], s[88:89], 0, v[80:81]
	global_load_lds_dwordx4 v[80:81], off
	v_lshl_add_u64 v[80:81], s[90:91], 0, v[84:85]
	s_mov_b32 m0, s8
	v_mov_b32_e32 v83, v145
	global_load_lds_dwordx4 v[80:81], off
	v_lshl_add_u64 v[80:81], s[88:89], 0, v[86:87]
	s_add_i32 m0, s99, 0x400
	s_nop 0
	global_load_lds_dwordx4 v[80:81], off
	v_lshl_add_u64 v[80:81], v[82:83], 1, s[90:91]
	s_add_i32 m0, s99, 0x4400
	s_nop 0
	global_load_lds_dwordx4 v[80:81], off
	s_waitcnt vmcnt(14)
	v_max_f32_e32 v0, v0, v0
	s_waitcnt vmcnt(13)
	v_max_f32_e32 v1, v1, v1
	v_max_f32_e32 v0, v1, v0
	s_waitcnt vmcnt(11)
	v_max3_f32 v0, v2, v3, v0
	ds_bpermute_b32 v1, v135, v0
	s_waitcnt lgkmcnt(0)
	v_max_f32_e32 v1, v1, v1
	v_max_f32_e32 v0, v0, v1
	ds_bpermute_b32 v1, v142, v0
	s_waitcnt lgkmcnt(0)
	v_max_f32_e32 v1, v1, v1
	v_max_f32_e32 v0, v0, v1
	ds_bpermute_b32 v1, v143, v0
	s_waitcnt lgkmcnt(0)
	v_max_f32_e32 v1, v1, v1
	v_max_f32_e32 v0, v0, v1
	ds_bpermute_b32 v1, v160, v0
	s_waitcnt lgkmcnt(0)
	v_max_f32_e32 v1, v1, v1
	v_max_f32_e32 v0, v0, v1
	ds_bpermute_b32 v1, v161, v0
	s_waitcnt lgkmcnt(0)
	v_max_f32_e32 v1, v1, v1
	v_max_f32_e32 v0, v0, v1
	ds_bpermute_b32 v1, v162, v0
	s_waitcnt lgkmcnt(0)
	v_max_f32_e32 v1, v1, v1
	v_max_f32_e32 v0, v0, v1
	v_add_f32_e32 v0, v164, v0
	v_add_f32_e32 v2, 0x3e800000, v0
	v_cmp_ge_f32_e32 vcc, s0, v2
	s_and_saveexec_b64 s[0:1], vcc
	s_xor_b64 s[40:41], exec, s[0:1]
	s_cbranch_execz .LBB0_341
	v_mov_b32_e32 v0, v169
	s_nop 0
	v_readfirstlane_b32 s25, v0
	s_waitcnt vmcnt(8)
	v_sub_f32_e32 v102, v102, v2
	v_add_u32_e32 v101, s2, v100
	ds_write_b32 v101, v102
	v_cmp_gt_u32_e32 vcc, 0x100, v169
	s_and_saveexec_b64 s[0:1], vcc
	v_sub_f32_e32 v103, v103, v2
	ds_write_b32 v101, v103 offset:2048
	s_mov_b64 exec, s[0:1]
	s_ashr_i32 s1, s25, 6
	s_ashr_i32 s26, s25, 8
	s_and_b32 s24, s1, 3
	s_mul_i32 s6, s26, 0x180
	s_lshl_b32 s0, s24, 5
	s_ashr_i32 s7, s6, 31
	s_or_b32 s29, s0, s34
	s_lshl_b64 s[6:7], s[6:7], 2
	s_add_u32 s6, s10, s6
	s_addc_u32 s7, s11, s7
	v_and_b32_e32 v134, 31, v0
	s_or_b32 s22, s54, s29
	v_bfe_u32 v167, v0, 5, 1
	v_lshlrev_b32_e32 v144, 4, v167
	s_lshl_b32 s8, s1, 3
	v_bfe_u32 v13, v0, 2, 2
	v_and_b32_e32 v168, 63, v0
	v_lshlrev_b32_e32 v166, 3, v168
	v_bfe_u32 v12, v0, 4, 2
	v_and_b32_e32 v15, 32, v0
	v_and_b32_e32 v16, 24, v166
	v_lshlrev_b32_e32 v19, 4, v0
	v_mov_b32_e32 v9, v145
	v_mov_b32_e32 v5, v145
	v_mov_b32_e32 v7, v145
	s_add_i32 s0, s34, s0
	s_lshl_b32 s38, s73, 9
	v_mov_b32_e32 v176, 0
	s_mov_b32 s23, s55
	s_lshl_b32 s28, s73, 1
	s_addk_i32 s29, 0xff51
	v_lshlrev_b32_e32 v171, 8, v134
	s_addk_i32 s38, 0x200
	s_mov_b32 s39, 0
	s_mov_b32 s44, 0
	s_mov_b32 s45, 0
	s_cmp_lg_u64 s[30:31], 0
	s_cselect_b32 s45, 0, 2
	s_mov_b32 s56, 0
	v_mov_b32_e32 v22, v176
	v_mov_b32_e32 v23, v176
	v_mov_b32_e32 v24, v176
	v_mov_b32_e32 v25, v176
	v_mov_b32_e32 v26, v176
	v_mov_b32_e32 v27, v176
	v_mov_b32_e32 v28, v176
	v_mov_b32_e32 v29, v176
	v_mov_b32_e32 v30, v176
	v_mov_b32_e32 v31, v176
	v_mov_b32_e32 v32, 0
	v_mov_b32_e32 v33, v176
	v_mov_b32_e32 v34, v176
	v_mov_b32_e32 v35, v176
	v_mov_b32_e32 v36, v176
	v_mov_b32_e32 v37, v176
	v_mov_b32_e32 v38, v176
	v_mov_b32_e32 v39, v176
	v_mov_b32_e32 v40, v176
	v_mov_b32_e32 v41, v176
	v_mov_b32_e32 v42, v176
	v_mov_b32_e32 v43, v176
	v_mov_b32_e32 v44, v176
	v_mov_b32_e32 v45, v176
	v_mov_b32_e32 v46, v176
	v_mov_b32_e32 v47, v176
	v_mov_b32_e32 v48, 0
	v_mov_b32_e32 v49, v176
	v_mov_b32_e32 v50, v176
	v_mov_b32_e32 v51, v176
	v_mov_b32_e32 v52, v176
	v_mov_b32_e32 v53, v176
	v_mov_b32_e32 v54, v176
	v_mov_b32_e32 v55, v176
	v_mov_b32_e32 v56, v176
	v_mov_b32_e32 v57, v176
	v_mov_b32_e32 v58, v176
	v_mov_b32_e32 v59, v176
	v_mov_b32_e32 v60, v176
	v_mov_b32_e32 v61, v176
	v_mov_b32_e32 v62, v176
	v_mov_b32_e32 v63, v176
	s_waitcnt vmcnt(8)
	v_sub_f32_e32 v64, v104, v2
	v_or_b32_e32 v1, s22, v134
	v_mov_b64_e32 v[2:3], s[16:17]
	v_mad_u64_u32 v[2:3], s[6:7], v1, s70, v[2:3]
	s_lshl_b32 s6, s26, 6
	v_mad_i32_i24 v3, s55, v196, v3
	s_ashr_i32 s7, s6, 31
	v_lshl_add_u64 v[2:3], s[6:7], 1, v[2:3]
	v_lshl_add_u64 v[2:3], v[2:3], 0, v[144:145]
	v_lshrrev_b32_e32 v2, 2, v0
	s_and_b32 s6, s8, -16
	v_and_b32_e32 v14, 4, v2
	s_lshl_b32 s7, s1, 3
	s_and_b32 s7, s7, 8
	v_or3_b32 v2, v14, v13, s6
	v_or_b32_e32 v2, s7, v2
	v_mul_lo_u32 v2, v2, s35
	v_or3_b32 v4, v2, v15, v16
	v_or_b32_e32 v2, s8, v12
	v_bitop3_b32 v3, v12, v0, 15 bitop3:0x78
	v_and_b32_e32 v1, 15, v0
	v_mul_lo_u32 v2, v2, s35
	v_lshlrev_b32_e32 v17, 3, v3
	v_or_b32_e32 v8, v2, v17
	v_or_b32_e32 v2, 4, v12
	v_bitop3_b32 v1, v12, v1, 4 bitop3:0x36
	v_or_b32_e32 v2, s8, v2
	v_lshlrev_b32_e32 v18, 3, v1
	v_and_b32_e32 v1, 0xc0, v19
	v_lshlrev_b32_e32 v0, 1, v0
	v_mul_lo_u32 v2, v2, s35
	s_lshl_b32 s8, s1, 11
	v_and_b32_e32 v20, 32, v0
	v_add3_u32 v21, 0, v16, v1
	v_lshlrev_b64 v[0:1], 1, v[8:9]
	v_or_b32_e32 v6, v2, v18
	s_add_i32 s27, s8, 0
	v_lshl_add_u64 v[8:9], s[18:19], 0, v[0:1]
	v_or_b32_e32 v2, 64, v4
	s_add_i32 s8, s27, 0x4000
	v_lshl_add_u64 v[8:9], v[8:9], 0, s[36:37]
	s_mov_b32 m0, s27
	v_lshlrev_b64 v[4:5], 1, v[4:5]
	v_lshlrev_b64 v[6:7], 1, v[6:7]
	v_lshl_add_u64 v[8:9], s[20:21], 0, v[4:5]
	s_mov_b32 m0, s8
	v_lshl_add_u64 v[10:11], s[18:19], 0, v[6:7]
	v_lshl_add_u64 v[10:11], v[10:11], 0, s[36:37]
	s_add_i32 m0, s27, 0x400
	v_lshl_add_u64 v[8:9], v[8:9], 0, s[94:95]
	s_add_i32 m0, s27, 0x4400
	s_add_i32 s8, s27, 0xc000
	s_add_i32 m0, s27, 0x8000
	v_lshl_add_u64 v[0:1], s[88:89], 0, v[0:1]
	v_lshl_add_u64 v[0:1], s[90:91], 0, v[4:5]
	s_mov_b32 m0, s8
	v_mov_b32_e32 v3, v145
	v_lshl_add_u64 v[0:1], s[88:89], 0, v[6:7]
	s_add_i32 m0, s27, 0x8400
	s_lshl_b32 s8, s26, 7
	v_lshl_add_u64 v[0:1], v[2:3], 1, s[90:91]
	s_add_i32 m0, s27, 0xc400
	s_mul_i32 s1, s1, 0xc000
	v_or_b32_e32 v0, s8, v144
	v_and_b32_e32 v1, 0x70, v19
	v_bitop3_b32 v173, v0, v1, 32 bitop3:0x36
	v_bitop3_b32 v174, v0, v1, 64 bitop3:0x36
	v_bitop3_b32 v175, v0, v1, s64 bitop3:0x36
	v_or_b32_e32 v0, s6, v14
	v_or3_b32 v0, v0, s7, v13
	v_mul_lo_u32 v0, v0, s35
	v_bitop3_b32 v172, s8, v1, v144 bitop3:0x36
	v_add_u32_e32 v172, v172, v171
	v_add_u32_e32 v173, v173, v171
	v_add_u32_e32 v174, v174, v171
	v_add_u32_e32 v175, v175, v171
	v_or3_b32 v0, v0, v15, v16
	v_mov_b32_e32 v1, v145
	s_add_i32 s6, s1, 0x6000
	v_lshlrev_b64 v[136:137], 1, v[0:1]
	v_mov_b32_e32 v0, s6
	v_mad_u32_u24 v0, v12, s35, v0
	v_or_b32_e32 v0, v0, v18
	v_lshlrev_b32_e32 v138, 1, v0
	v_mov_b32_e32 v0, s1
	v_mad_u32_u24 v0, v12, s35, v0
	v_or_b32_e32 v0, v0, v17
	s_waitcnt vmcnt(4) lgkmcnt(0)
	s_barrier
; #define SBAR() __builtin_amdgcn_sched_barrier(0)
; #define SCORE(P0, P1, Kbuf, t, CADD) do { const int dmin_ = qw0 - 64 * (t) - 63; const bool far_ = dmin_ >= 113; CADD = (far_ && !FIXED) ? c31 : 0.f; \
;     if (FIXED && far_) { qkt(P0, P1, Kbuf, qr, r32, hi, m, cfar); } \
;     else { qkt(P0, P1, Kbuf, qr, r32, hi, m, czero); if (!far_) bias_mask(P0, P1, bt, qw0 + r32 - 64 * (t) - 4 * hi); } } while (0)
; __device__ __forceinline__ void qkt(f32x16& p0, f32x16& p1, const char* Ks, const bf16x8* qr, int r32, int hi, int m, const f32x16& cinit) {
;   bf16x8 kf[8];
; #pragma unroll
;   for (int d0 = 0; d0 < 4; ++d0) { const int cb = (m * 64 + d0 * 16 + hi * 8) * 2;
;     kf[2 * d0] = *reinterpret_cast<const bf16x8*>(Ks + KSWZ(r32, cb)); kf[2 * d0 + 1] = *reinterpret_cast<const bf16x8*>(Ks + KSWZ(32 + r32, cb)); }
;   SBAR();
;   p0 = __builtin_amdgcn_mfma_f32_32x32x16_bf16(kf[0], qr[0], cinit, 0, 0, 0);
;   p1 = __builtin_amdgcn_mfma_f32_32x32x16_bf16(kf[1], qr[0], cinit, 0, 0, 0);
; #pragma unroll
;   for (int d0 = 1; d0 < 4; ++d0) {
;     p0 = __builtin_amdgcn_mfma_f32_32x32x16_bf16(kf[2 * d0], qr[d0], p0, 0, 0, 0);
;     p1 = __builtin_amdgcn_mfma_f32_32x32x16_bf16(kf[2 * d0 + 1], qr[d0], p1, 0, 0, 0); }
;   SBAR();
; }
; __device__ __forceinline__ void bias_mask(f32x16& p0, f32x16& p1, const float* bt, int base) {
; #pragma unroll
;   for (int r = 0; r < 16; ++r) { const int c = (r & 3) + 8 * (r >> 2); p0[r] += bt[base - c]; }
;   SBAR();
; #pragma unroll
;   for (int r = 0; r < 16; ++r) { const int c = (r & 3) + 8 * (r >> 2); p1[r] += bt[base - c - 32]; }
; }
; template <bool FIXED> __device__ __forceinline__ void attn_unit(int b, int h, int qb, const bf16* __restrict__ P, bf16* __restrict__ MIX, const float* __restrict__ BT, const float* __restrict__ subg, ...
;     ...
;   for (int tt = 0; tt < NTT; ++tt) {
;     const int t = (ATT_REP == 1) ? tt : (tt % NT), t2 = (ATT_REP == 1) ? tt + 2 : ((tt + 2) % NT);
;     const int s2 = (slot >= 1) ? slot - 1 : 2;
;     if (tt + 2 < NTT) DMA_TILE(t2, s2);
;     SBAR();
;     ...
; #pragma unroll 1
;     for (int crep = 0; crep < ATT_CREP; ++crep) {
;     SCORE(p0, p1, lds + slot * SLOTB, t, ca);
	v_lshlrev_b32_e32 v2, 2, v167
	v_lshlrev_b32_e32 v140, 1, v0
	s_mul_i32 s1, s26, 0x600
	v_add_u32_e32 v0, s0, v134
	v_and_b32_e32 v8, 0x100, v166
	v_sub_u32_e32 v0, v0, v2
	s_add_i32 s0, s1, 0
	v_mov_b32_e32 v65, v64
	v_mov_b32_e32 v66, v64
	v_mov_b32_e32 v67, v64
	v_mov_b32_e32 v68, v64
	v_mov_b32_e32 v69, v64
	v_mov_b32_e32 v70, v64
	v_mov_b32_e32 v71, v64
	v_mov_b32_e32 v72, v64
	v_mov_b32_e32 v73, v64
	v_mov_b32_e32 v74, v64
	v_mov_b32_e32 v75, v64
	v_mov_b32_e32 v76, v64
	v_mov_b32_e32 v77, v64
	v_mov_b32_e32 v78, v64
	v_mov_b32_e32 v79, v64
	v_add3_u32 v170, v21, v20, v8
	v_lshl_add_u32 v178, v0, 2, s0
	s_mov_b64 s[0:1], s[92:93]
	v_mov_b32_e32 v0, 0
	v_mov_b32_e32 v1, v176
	v_mov_b32_e32 v2, v176
	v_mov_b32_e32 v3, v176
	v_mov_b32_e32 v4, v176
	v_mov_b32_e32 v5, v176
	v_mov_b32_e32 v6, v176
	v_mov_b32_e32 v7, v176
	v_mov_b32_e32 v8, v176
	v_mov_b32_e32 v9, v176
	v_mov_b32_e32 v10, v176
	v_mov_b32_e32 v11, v176
	v_mov_b32_e32 v12, v176
	v_mov_b32_e32 v13, v176
	v_mov_b32_e32 v14, v176
	v_mov_b32_e32 v15, v176
	v_mov_b32_e32 v16, 0
	v_mov_b32_e32 v17, v176
	v_mov_b32_e32 v18, v176
	v_mov_b32_e32 v19, v176
	v_mov_b32_e32 v20, v176
	v_mov_b32_e32 v21, v176
	s_lshl_b32 s59, s45, 15
	s_add_i32 s9, s59, 0xffff8000
	s_cmp_gt_i32 s45, 0
	s_cselect_b32 s9, s9, 0x10000
	s_add_i32 s9, s27, s9
	s_add_u32 s98, s0, 0x1a380800
	s_addc_u32 s99, s1, 0
	s_add_u32 s100, s0, s4
	s_addc_u32 s101, s1, s5
	s_waitcnt vmcnt(4)
	s_branch .LBB0_312
.LBB0_312:
	s_cmp_ge_u32 s56, s28
	s_cbranch_scc1 .LBB0_316
	s_mov_b32 m0, s9
	s_nop 0
	global_load_lds_dwordx4 v140, s[98:99]
	s_add_i32 m0, s9, 0x4000
	s_nop 0
	global_load_lds_dwordx4 v136, s[100:101]
	s_add_i32 m0, s9, 0x400
	s_add_u32 s100, s0, s74
	s_addc_u32 s101, s1, s75
	global_load_lds_dwordx4 v138, s[98:99]
	s_add_i32 m0, s9, 0x4400
	s_nop 0
	global_load_lds_dwordx4 v136, s[100:101]
.LBB0_316:
	s_cmp_ge_i32 s39, s29
	s_cbranch_scc0 .Ledge_far
	v_add_u32_e32 v85, s59, v172
	v_add_u32_e32 v87, s59, v173
	v_add_u32_e32 v89, s59, v174
	v_add_u32_e32 v91, s59, v175
	ds_read_b128 v[80:83], v85
	ds_read_b128 v[96:99], v85 offset:8192
	ds_read_b128 v[198:201], v87
	ds_read_b128 v[202:205], v87 offset:8192
	ds_read_b128 v[206:209], v89
	ds_read_b128 v[210:213], v89 offset:8192
	ds_read_b128 v[214:217], v91
	ds_read_b128 v[218:221], v91 offset:8192
	v_add_u32_e32 v230, s44, v178
	v_add_u32_e32 v230, 0x18914, v230
	s_waitcnt lgkmcnt(0)
	v_mfma_f32_32x32x16_bf16 v[80:95], v[80:83], v[112:115], 0
	v_mfma_f32_32x32x16_bf16 v[96:111], v[96:99], v[112:115], 0
	v_mfma_f32_32x32x16_bf16 v[80:95], v[198:201], v[116:119], v[80:95]
	v_mfma_f32_32x32x16_bf16 v[96:111], v[202:205], v[116:119], v[96:111]
	v_mfma_f32_32x32x16_bf16 v[80:95], v[206:209], v[120:123], v[80:95]
	v_mfma_f32_32x32x16_bf16 v[96:111], v[210:213], v[120:123], v[96:111]
	v_mfma_f32_32x32x16_bf16 v[80:95], v[214:217], v[124:127], v[80:95]
	v_mfma_f32_32x32x16_bf16 v[96:111], v[218:221], v[124:127], v[96:111]
	ds_read2_b32 v[198:199], v230 offset0:58 offset1:59
	ds_read2_b32 v[200:201], v230 offset0:56 offset1:57
	ds_read2_b32 v[202:203], v230 offset0:50 offset1:51
	ds_read2_b32 v[204:205], v230 offset0:48 offset1:49
	ds_read2_b32 v[206:207], v230 offset0:42 offset1:43
	ds_read2_b32 v[208:209], v230 offset0:40 offset1:41
	ds_read2_b32 v[210:211], v230 offset0:34 offset1:35
	ds_read2_b32 v[212:213], v230 offset0:32 offset1:33
	ds_read2_b32 v[214:215], v230 offset0:26 offset1:27
	ds_read2_b32 v[216:217], v230 offset0:24 offset1:25
	ds_read2_b32 v[218:219], v230 offset0:18 offset1:19
	ds_read2_b32 v[220:221], v230 offset0:16 offset1:17
	ds_read2_b32 v[222:223], v230 offset0:10 offset1:11
	ds_read2_b32 v[224:225], v230 offset0:8 offset1:9
	ds_read2_b32 v[226:227], v230 offset0:2 offset1:3
	ds_read2_b32 v[228:229], v230 offset0:0 offset1:1
	s_waitcnt lgkmcnt(0)
	v_add_f32_e32 v80, v80, v199
	v_add_f32_e32 v81, v81, v198
	v_pk_add_f32 v[82:83], v[82:83], v[200:201] op_sel:[0,1] op_sel_hi:[1,0]
	v_pk_add_f32 v[84:85], v[84:85], v[202:203] op_sel:[0,1] op_sel_hi:[1,0]
	v_pk_add_f32 v[86:87], v[86:87], v[204:205] op_sel:[0,1] op_sel_hi:[1,0]
	v_pk_add_f32 v[88:89], v[88:89], v[206:207] op_sel:[0,1] op_sel_hi:[1,0]
	v_pk_add_f32 v[90:91], v[90:91], v[208:209] op_sel:[0,1] op_sel_hi:[1,0]
	v_pk_add_f32 v[92:93], v[92:93], v[210:211] op_sel:[0,1] op_sel_hi:[1,0]
	v_pk_add_f32 v[94:95], v[94:95], v[212:213] op_sel:[0,1] op_sel_hi:[1,0]
	v_pk_add_f32 v[96:97], v[96:97], v[214:215] op_sel:[0,1] op_sel_hi:[1,0]
	v_pk_add_f32 v[98:99], v[98:99], v[216:217] op_sel:[0,1] op_sel_hi:[1,0]
	v_pk_add_f32 v[100:101], v[100:101], v[218:219] op_sel:[0,1] op_sel_hi:[1,0]
	v_pk_add_f32 v[102:103], v[102:103], v[220:221] op_sel:[0,1] op_sel_hi:[1,0]
	v_pk_add_f32 v[104:105], v[104:105], v[222:223] op_sel:[0,1] op_sel_hi:[1,0]
	v_pk_add_f32 v[106:107], v[106:107], v[224:225] op_sel:[0,1] op_sel_hi:[1,0]
	v_pk_add_f32 v[108:109], v[108:109], v[226:227] op_sel:[0,1] op_sel_hi:[1,0]
	v_pk_add_f32 v[110:111], v[110:111], v[228:229] op_sel:[0,1] op_sel_hi:[1,0]
	s_branch .LBB0_320
.Ledge_far:
	v_add_u32_e32 v80, s59, v172
	v_add_u32_e32 v81, s59, v173
	v_add_u32_e32 v82, s59, v174
	v_add_u32_e32 v83, s59, v175
	ds_read_b128 v[96:99], v80
	ds_read_b128 v[198:201], v80 offset:8192
	ds_read_b128 v[202:205], v81
	ds_read_b128 v[206:209], v81 offset:8192
	ds_read_b128 v[210:213], v82
	ds_read_b128 v[214:217], v82 offset:8192
	ds_read_b128 v[218:221], v83
	ds_read_b128 v[222:225], v83 offset:8192
	s_waitcnt lgkmcnt(0)
	v_mfma_f32_32x32x16_bf16 v[80:95], v[96:99], v[112:115], v[64:79]
	v_mfma_f32_32x32x16_bf16 v[96:111], v[198:201], v[112:115], v[64:79]
	v_mfma_f32_32x32x16_bf16 v[80:95], v[202:205], v[116:119], v[80:95]
	v_mfma_f32_32x32x16_bf16 v[96:111], v[206:209], v[116:119], v[96:111]
	v_mfma_f32_32x32x16_bf16 v[80:95], v[210:213], v[120:123], v[80:95]
	v_mfma_f32_32x32x16_bf16 v[96:111], v[214:217], v[120:123], v[96:111]
	v_mfma_f32_32x32x16_bf16 v[80:95], v[218:221], v[124:127], v[80:95]
	v_mfma_f32_32x32x16_bf16 v[96:111], v[222:225], v[124:127], v[96:111]
; #define SBAR() __builtin_amdgcn_sched_barrier(0)
; __device__ __forceinline__ void finishSM(f32x16& p0, f32x16& p1, float alpha, float& l_reg, bf16x8& pa0, bf16x8& pa1, bf16x8& pa2, bf16x8& pa3) {
; #pragma unroll
;   for (int r = 0; r < 16; ++r) p1[r] = __builtin_amdgcn_exp2f(p1[r]);
;   float ps = 0;
; #pragma unroll
;   for (int r = 0; r < 16; ++r) ps += p0[r];
; #pragma unroll
;   for (int r = 0; r < 16; ++r) ps += p1[r];
;   { auto rr = __builtin_amdgcn_permlane32_swap(__float_as_uint(ps), __float_as_uint(ps), false, false);
;     ps = __uint_as_float(rr[0]) + __uint_as_float(rr[1]); }
;   l_reg = l_reg * alpha + ps;
;     ...
;   PK4(p0, 0, pa0); PK4(p0, 8, pa1); PK4(p1, 0, pa2); PK4(p1, 8, pa3);
; __device__ __forceinline__ void pv_all(f32x16* o, lds_cptr vp, bf16x8 pa0, bf16x8 pa1, bf16x8 pa2, bf16x8 pa3) {
;   VFrag fa, fb;
;   v_read<0>(fa, vp); v_read<1>(fb, vp); SBAR();
;   pv_slice(o, fa, pa0); SBAR(); v_read<2>(fa, vp); SBAR();
;   pv_slice(o, fb, pa1); SBAR(); v_read<3>(fb, vp); SBAR();
;   pv_slice(o, fa, pa2); SBAR();
;   pv_slice(o, fb, pa3); SBAR();
; }
.LBB0_320:
	v_add_u32_e32 v244, s59, v170
	ds_read_b64_tr_b16 v[232:233], v244 offset:16384
	ds_read_b64_tr_b16 v[236:237], v244 offset:16896
	ds_read_b64_tr_b16 v[240:241], v244 offset:17408
	ds_read_b64_tr_b16 v[198:199], v244 offset:17920
	ds_read_b64_tr_b16 v[234:235], v244 offset:18432
	ds_read_b64_tr_b16 v[238:239], v244 offset:18944
	ds_read_b64_tr_b16 v[242:243], v244 offset:19456
	ds_read_b64_tr_b16 v[200:201], v244 offset:19968
	ds_read_b64_tr_b16 v[202:203], v244 offset:20480
	ds_read_b64_tr_b16 v[206:207], v244 offset:20992
	ds_read_b64_tr_b16 v[210:211], v244 offset:21504
	ds_read_b64_tr_b16 v[214:215], v244 offset:22016
	ds_read_b64_tr_b16 v[204:205], v244 offset:22528
	ds_read_b64_tr_b16 v[208:209], v244 offset:23040
	ds_read_b64_tr_b16 v[212:213], v244 offset:23552
	ds_read_b64_tr_b16 v[216:217], v244 offset:24064
	s_nop 1
	v_exp_f32_e32 v179, v80
	v_exp_f32_e32 v180, v81
	v_exp_f32_e32 v181, v82
	v_exp_f32_e32 v83, v83
	v_add_f32_e32 v80, 0, v179
	v_exp_f32_e32 v84, v84
	v_add_f32_e32 v80, v180, v80
	v_exp_f32_e32 v85, v85
	v_add_f32_e32 v80, v181, v80
	v_exp_f32_e32 v86, v86
	v_add_f32_e32 v80, v83, v80
	v_exp_f32_e32 v87, v87
	v_add_f32_e32 v80, v84, v80
	v_add_f32_e32 v80, v85, v80
	v_add_f32_e32 v80, v86, v80
	v_add_f32_e32 v80, v87, v80
	v_cvt_pk_bf16_f32 v82, v179, v180
	v_cvt_pk_bf16_f32 v83, v181, v83
	v_cvt_pk_bf16_f32 v84, v84, v85
	v_cvt_pk_bf16_f32 v85, v86, v87
	ds_read_b64_tr_b16 v[246:247], v244 offset:24576
	ds_read_b64_tr_b16 v[218:219], v244 offset:25088
	ds_read_b64_tr_b16 v[222:223], v244 offset:25600
	ds_read_b64_tr_b16 v[250:251], v244 offset:26112
	ds_read_b64_tr_b16 v[248:249], v244 offset:26624
	ds_read_b64_tr_b16 v[220:221], v244 offset:27136
	ds_read_b64_tr_b16 v[224:225], v244 offset:27648
	ds_read_b64_tr_b16 v[252:253], v244 offset:28160
	s_waitcnt lgkmcnt(8)
	v_exp_f32_e32 v88, v88
	v_mfma_f32_32x32x16_bf16 v[0:15], v[82:85], v[232:235], v[0:15]
	v_exp_f32_e32 v89, v89
	v_exp_f32_e32 v90, v90
	v_add_f32_e32 v80, v88, v80
	v_exp_f32_e32 v91, v91
	v_add_f32_e32 v80, v89, v80
	v_mfma_f32_32x32x16_bf16 v[16:31], v[82:85], v[236:239], v[16:31]
	v_exp_f32_e32 v92, v92
	v_add_f32_e32 v80, v90, v80
	v_exp_f32_e32 v93, v93
	v_add_f32_e32 v80, v91, v80
	v_exp_f32_e32 v94, v94
	v_add_f32_e32 v80, v92, v80
	v_mfma_f32_32x32x16_bf16 v[32:47], v[82:85], v[240:243], v[32:47]
	v_exp_f32_e32 v95, v95
	v_add_f32_e32 v80, v93, v80
	v_add_f32_e32 v80, v94, v80
	v_add_f32_e32 v80, v95, v80
	v_cvt_pk_bf16_f32 v86, v88, v89
	v_cvt_pk_bf16_f32 v87, v90, v91
	v_mfma_f32_32x32x16_bf16 v[48:63], v[82:85], v[198:201], v[48:63]
	v_cvt_pk_bf16_f32 v88, v92, v93
	v_cvt_pk_bf16_f32 v89, v94, v95
	s_nop 0
	v_exp_f32_e32 v96, v96
	v_exp_f32_e32 v97, v97
	v_mfma_f32_32x32x16_bf16 v[0:15], v[86:89], v[202:205], v[0:15]
	v_exp_f32_e32 v98, v98
	v_add_f32_e32 v80, v96, v80
	v_exp_f32_e32 v99, v99
	v_add_f32_e32 v80, v97, v80
	v_exp_f32_e32 v100, v100
	v_add_f32_e32 v80, v98, v80
	v_mfma_f32_32x32x16_bf16 v[16:31], v[86:89], v[206:209], v[16:31]
	v_exp_f32_e32 v101, v101
	v_add_f32_e32 v80, v99, v80
	v_exp_f32_e32 v102, v102
	v_add_f32_e32 v80, v100, v80
	v_exp_f32_e32 v103, v103
	v_add_f32_e32 v80, v101, v80
	v_mfma_f32_32x32x16_bf16 v[32:47], v[86:89], v[210:213], v[32:47]
	v_add_f32_e32 v80, v102, v80
	v_add_f32_e32 v80, v103, v80
	v_cvt_pk_bf16_f32 v90, v96, v97
	v_cvt_pk_bf16_f32 v91, v98, v99
	v_cvt_pk_bf16_f32 v92, v100, v101
	v_mfma_f32_32x32x16_bf16 v[48:63], v[86:89], v[214:217], v[48:63]
	v_cvt_pk_bf16_f32 v93, v102, v103
	ds_read_b64_tr_b16 v[86:87], v244 offset:28672
	ds_read_b64_tr_b16 v[198:199], v244 offset:29184
	ds_read_b64_tr_b16 v[202:203], v244 offset:29696
	ds_read_b64_tr_b16 v[206:207], v244 offset:30208
	ds_read_b64_tr_b16 v[88:89], v244 offset:30720
	ds_read_b64_tr_b16 v[200:201], v244 offset:31232
	ds_read_b64_tr_b16 v[204:205], v244 offset:31744
	ds_read_b64_tr_b16 v[208:209], v244 offset:32256
	s_waitcnt lgkmcnt(8)
	v_exp_f32_e32 v104, v104
	v_exp_f32_e32 v105, v105
	v_mfma_f32_32x32x16_bf16 v[0:15], v[90:93], v[246:249], v[0:15]
	v_exp_f32_e32 v106, v106
	v_add_f32_e32 v80, v104, v80
	v_exp_f32_e32 v107, v107
	v_add_f32_e32 v80, v105, v80
	v_exp_f32_e32 v108, v108
	v_add_f32_e32 v80, v106, v80
	v_mfma_f32_32x32x16_bf16 v[16:31], v[90:93], v[218:221], v[16:31]
	v_exp_f32_e32 v109, v109
	v_add_f32_e32 v80, v107, v80
	v_exp_f32_e32 v110, v110
	v_add_f32_e32 v80, v108, v80
	v_exp_f32_e32 v111, v111
	v_add_f32_e32 v80, v109, v80
	v_mfma_f32_32x32x16_bf16 v[32:47], v[90:93], v[222:225], v[32:47]
	v_add_f32_e32 v80, v110, v80
	v_add_f32_e32 v80, v111, v80
	v_cvt_pk_bf16_f32 v94, v104, v105
	v_cvt_pk_bf16_f32 v95, v106, v107
	v_cvt_pk_bf16_f32 v96, v108, v109
	v_mfma_f32_32x32x16_bf16 v[48:63], v[90:93], v[250:253], v[48:63]
	v_cvt_pk_bf16_f32 v97, v110, v111
	v_mov_b32_e32 v81, v80
	s_nop 1
	s_waitcnt lgkmcnt(0)
	v_permlane32_swap_b32_e32 v80, v81
	v_mfma_f32_32x32x16_bf16 v[0:15], v[94:97], v[86:89], v[0:15]
	s_add_i32 s6, s45, 1
	s_cmp_lg_u32 s45, 2
	s_cselect_b32 s45, s6, 0
	s_add_i32 s56, s56, 1
	s_add_u32 s0, s0, 0xc0000
	s_addc_u32 s1, s1, 0
	s_addk_i32 s44, 0xff00
	s_add_i32 s39, s39, 64
	v_mfma_f32_32x32x16_bf16 v[16:31], v[94:97], v[198:201], v[16:31]
	s_lshl_b32 s59, s45, 15
	s_add_i32 s9, s59, 0xffff8000
	s_cmp_gt_i32 s45, 0
	s_cselect_b32 s9, s9, 0x10000
	s_add_i32 s9, s27, s9
	v_mfma_f32_32x32x16_bf16 v[32:47], v[94:97], v[202:205], v[32:47]
	s_add_u32 s98, s0, 0x1a380800
	s_addc_u32 s99, s1, 0
	s_add_u32 s100, s0, s4
	s_addc_u32 s101, s1, s5
	v_mfma_f32_32x32x16_bf16 v[48:63], v[94:97], v[206:209], v[48:63]
	v_add_f32_e32 v80, v80, v81
	s_add_i32 s6, s38, s44
	s_cmp_eq_u32 s6, 0
	v_add_f32_e32 v176, v176, v80
	s_cbranch_scc1 .Ledge_exit
	s_cmp_le_u32 s56, s28
	s_cbranch_scc0 .Ledge_w0
	s_waitcnt vmcnt(4) lgkmcnt(0)
	s_barrier
	s_branch .LBB0_312
.Ledge_w0:
	s_waitcnt vmcnt(0) lgkmcnt(0)
	s_barrier
	s_branch .LBB0_312
.Ledge_exit:
	s_waitcnt vmcnt(0) lgkmcnt(0)
	s_barrier
